# FFN1-in and FFN2-in GEMMs walk the tile list in reverse (newest producer rows first; written ACT consumed newest-first by the out GEMM)
# speedup vs baseline: 1.0046x; 1.0011x over previous
.LBB0_166:
	s_or_b64 exec, exec, s[0:1]
	v_writelane_b32 v252, s56, 18
	v_writelane_b32 v252, s60, 19
	v_mov_b32_e32 v139, v210
	s_mov_b32 s46, s90
	s_mov_b32 s47, s56
	s_mov_b64 s[4:5], s[88:89]
	v_writelane_b32 v252, s61, 20
	s_waitcnt lgkmcnt(0)
	s_barrier
	v_writelane_b32 v252, s62, 21
	v_writelane_b32 v252, s63, 22
	s_mov_b64 s[0:1], s[64:65]
	s_mov_b64 s[8:9], s[72:73]
	v_writelane_b32 v252, s0, 23
	v_readfirstlane_b32 s27, v139
	s_cmpk_gt_i32 s47, 0x15ff
	v_writelane_b32 v252, s1, 24
	v_writelane_b32 v252, s2, 25
	v_writelane_b32 v252, s3, 26
	v_writelane_b32 v252, s4, 27
	v_writelane_b32 v252, s5, 28
	v_writelane_b32 v252, s6, 29
	v_writelane_b32 v252, s7, 30
	v_writelane_b32 v252, s8, 31
	v_writelane_b32 v252, s9, 32
	v_writelane_b32 v252, s10, 33
	v_writelane_b32 v252, s11, 34
	v_writelane_b32 v252, s12, 35
	v_writelane_b32 v252, s13, 36
	v_writelane_b32 v252, s14, 37
	v_writelane_b32 v252, s15, 38
	s_cbranch_scc1 .LBB0_182
	v_bfe_i32 v1, v139, 27, 1
	v_lshlrev_b32_e32 v0, 4, v139
	v_lshrrev_b32_e32 v1, 22, v1
	v_add_u32_e32 v1, v0, v1
	v_and_b32_e32 v1, 0xfffffc00, v1
	v_sub_u32_e32 v0, v0, v1
	v_lshrrev_b32_e32 v1, 4, v0
	v_ashrrev_i32_e32 v3, 31, v139
	v_bitop3_b32 v0, v1, v0, 32 bitop3:0x6c
	v_lshrrev_b32_e32 v3, 26, v3
	s_ashr_i32 s28, s27, 6
	v_ashrrev_i32_e32 v1, 31, v0
	v_add_u32_e32 v3, v139, v3
	s_add_u32 s48, s4, 0x4000000
	v_lshrrev_b32_e32 v1, 26, v1
	v_ashrrev_i32_e32 v3, 6, v3
	s_addc_u32 s49, s5, 0
	v_add_u32_e32 v1, v0, v1
	v_lshlrev_b32_e32 v4, 3, v3
	s_add_u32 s51, s4, 0x600000
	v_ashrrev_i32_e32 v2, 6, v1
	v_and_b32_e32 v4, -16, v4
	s_addc_u32 s52, s5, 0
	v_add_u32_e32 v4, v2, v4
	v_and_b32_e32 v2, 3, v2
	s_mov_b32 s0, 0x1fffe0
	s_sub_i32 s98, 0x15ff, s47
	s_ashr_i32 s54, s47, 31
	v_and_or_b32 v2, v4, s0, v2
	s_lshr_b32 s0, s54, 29
	s_add_i32 s0, s98, s0
	s_ashr_i32 s1, s0, 3
	s_and_b32 s0, s0, -8
	s_ashr_i32 s29, s27, 8
	s_lshl_b32 s53, s28, 10
	s_sub_i32 s0, s98, s0
	s_cmp_lt_i32 s0, 0
	s_movk_i32 s55, 0x2c1
	s_cselect_b32 s2, s55, 0x2c0
	s_mul_i32 s0, s0, s2
	s_add_i32 s0, s0, s1
	s_mul_hi_i32 s1, s0, 0x2e8ba2e9
	s_lshr_b32 s2, s1, 31
	s_ashr_i32 s1, s1, 5
	s_add_i32 s1, s1, s2
	s_lshl_b32 s2, s1, 3
	s_mulk_i32 s1, 0xb0
	s_sub_i32 s0, s0, s1
	s_bfe_u32 s1, s0, 0x3001c
	s_add_i32 s1, s0, s1
	s_sext_i32_i16 s3, s1
	s_and_b32 s1, s1, 0xfff8
	s_sub_i32 s0, s0, s1
	v_and_b32_e32 v1, 0xc0, v1
	s_sext_i32_i16 s0, s0
	v_sub_u32_e32 v0, v0, v1
	v_mov_b32_e32 v1, 1
	s_lshr_b32 s26, s3, 3
	s_add_i32 s38, s2, s0
	v_lshrrev_b32_e32 v5, 2, v4
	v_lshlrev_b32_e32 v6, 1, v4
	v_lshlrev_b32_e32 v3, 5, v3
	v_ashrrev_i16_sdwa v0, v1, sext(v0) dst_sel:DWORD dst_unused:UNUSED_PAD src0_sel:DWORD src1_sel:BYTE_0
	s_ashr_i32 s39, s38, 31
	s_bfe_i64 s[0:1], s[26:27], 0x100000
	v_and_b32_e32 v5, 4, v5
	v_and_b32_e32 v6, 24, v6
	v_and_b32_e32 v3, 32, v3
	v_bfe_i32 v0, v0, 0, 16
	s_lshl_b64 s[14:15], s[38:39], 19
	s_lshl_b64 s[0:1], s[0:1], 19
	v_or3_b32 v2, v2, v5, v6
	v_add_lshl_u32 v0, v3, v0, 1
	s_add_u32 s40, s51, s0
	v_lshl_add_u32 v128, v2, 11, v0
	s_addc_u32 s41, s52, s1
	v_mov_b32_e32 v129, 0
	s_add_i32 s39, s53, 0
	v_lshl_add_u32 v130, v4, 11, v0
	v_lshl_add_u64 v[0:1], s[40:41], 0, v[128:129]
	s_add_i32 m0, s39, 0x10000
	s_mov_b64 s[0:1], 0x20000
	global_load_lds_dwordx4 v128, s[40:41]
	v_lshl_add_u64 v[2:3], v[0:1], 0, s[0:1]
	s_add_i32 m0, s39, 0x12000
	s_mov_b64 s[2:3], 0x40000
	global_load_lds_dwordx4 v[2:3], off
	v_lshl_add_u64 v[2:3], v[0:1], 0, s[2:3]
	s_add_i32 m0, s39, 0x14000
	s_mov_b64 s[8:9], 0x60000
	global_load_lds_dwordx4 v[2:3], off
	s_add_i32 m0, s39, 0x16000
	s_add_u32 s42, s48, s14
	v_lshl_add_u64 v[2:3], v[0:1], 0, s[8:9]
	s_addc_u32 s43, s49, s15
	v_mov_b32_e32 v131, v129
	global_load_lds_dwordx4 v[2:3], off
	v_lshl_add_u64 v[2:3], s[42:43], 0, v[130:131]
	s_mov_b32 m0, s39
	s_add_i32 s56, s39, 0x2000
	global_load_lds_dwordx4 v130, s[42:43]
	v_lshl_add_u64 v[4:5], v[2:3], 0, s[0:1]
	s_mov_b32 m0, s56
	s_add_i32 s57, s39, 0x4000
	global_load_lds_dwordx4 v[4:5], off
	v_lshl_add_u64 v[4:5], v[2:3], 0, s[2:3]
	s_mov_b32 m0, s57
	s_add_i32 s58, s39, 0x6000
	global_load_lds_dwordx4 v[4:5], off
	v_lshl_add_u64 v[4:5], v[2:3], 0, s[8:9]
	s_mov_b32 m0, s58
	s_cmp_eq_u32 s29, 1
	global_load_lds_dwordx4 v[4:5], off
	s_cselect_b64 s[14:15], -1, 0
	s_cmp_lg_u32 s29, 1
	s_mov_b32 s59, 0
	s_cbranch_scc1 .LBB0_169
	s_barrier

.LBB0_172:
	s_add_i32 s59, s59, 1
	s_mul_i32 s4, s59, s64
	s_mul_hi_u32 s5, s59, s46
	s_add_i32 s5, s5, s4
	s_mul_i32 s4, s59, s46
	s_add_u32 s34, s4, s47
	s_addc_u32 s35, s5, s54
	v_cmp_gt_i64_e32 vcc, s[34:35], v[134:135]
	v_cmp_lt_i64_e64 s[4:5], s[34:35], v[132:133]
	s_cbranch_vccnz .LBB0_174
	s_sub_i32 s34, 0x15ff, s34
	s_ashr_i32 s28, s34, 31
	s_lshr_b32 s28, s28, 29
	s_add_i32 s28, s34, s28
	s_ashr_i32 s29, s28, 3
	s_and_b32 s28, s28, -8
	s_sub_i32 s28, s34, s28
	s_cmp_lt_i32 s28, 0
	s_cselect_b32 s30, s55, 0x2c0
	s_mul_i32 s28, s28, s30
	s_add_i32 s28, s28, s29
	s_mul_hi_i32 s29, s28, 0x2e8ba2e9
	s_lshr_b32 s30, s29, 31
	s_ashr_i32 s29, s29, 5
	s_add_i32 s29, s29, s30
	s_lshl_b32 s30, s29, 3
	s_sub_i32 s31, 0x100, s30
	s_min_i32 s31, s31, 8
	s_abs_i32 s34, s31
	v_cvt_f32_u32_e32 v0, s34
	s_sub_i32 s36, 0, s34
	s_mulk_i32 s29, 0xb0
	s_sub_i32 s29, s28, s29
	v_rcp_iflag_f32_e32 v0, v0
	s_abs_i32 s28, s29
	s_xor_b32 s35, s29, s31
	s_ashr_i32 s35, s35, 31
	v_mul_f32_e32 v0, 0x4f7ffffe, v0
	v_cvt_u32_f32_e32 v0, v0
	s_nop 0
	v_readfirstlane_b32 s37, v0
	s_mul_i32 s36, s36, s37
	s_mul_hi_u32 s36, s37, s36
	s_add_i32 s37, s37, s36
	s_mul_hi_u32 s36, s28, s37
	s_mul_i32 s37, s36, s34
	s_sub_i32 s28, s28, s37
	s_add_i32 s44, s36, 1
	s_sub_i32 s37, s28, s34
	s_cmp_ge_u32 s28, s34
	s_cselect_b32 s36, s44, s36
	s_cselect_b32 s28, s37, s28
	s_add_i32 s37, s36, 1
	s_cmp_ge_u32 s28, s34
	s_cselect_b32 s28, s37, s36
	s_xor_b32 s28, s28, s35
	s_sub_i32 s28, s28, s35
	s_mul_i32 s31, s28, s31
	s_sub_i32 s29, s29, s31
	s_add_i32 s30, s30, s29

.LBB0_961:
	s_or_b64 exec, exec, s[0:1]
	v_readlane_b32 s0, v252, 39
	v_mov_b32_e32 v138, v210
	s_mov_b32 s33, s0
	s_mov_b32 s40, s64
	s_mov_b64 s[8:9], s[88:89]
	s_waitcnt lgkmcnt(0)
	s_barrier
	s_cmpk_gt_i32 s40, 0x15ff
	v_readfirstlane_b32 s19, v138
	v_readlane_b32 s1, v252, 40
	s_cbranch_scc1 .LBB0_977
	v_bfe_i32 v1, v138, 27, 1
	v_lshlrev_b32_e32 v0, 4, v138
	v_lshrrev_b32_e32 v1, 22, v1
	v_add_u32_e32 v1, v0, v1
	v_and_b32_e32 v1, 0xfffffc00, v1
	v_sub_u32_e32 v0, v0, v1
	v_lshrrev_b32_e32 v1, 4, v0
	v_ashrrev_i32_e32 v3, 31, v138
	v_bitop3_b32 v0, v1, v0, 32 bitop3:0x6c
	v_lshrrev_b32_e32 v3, 26, v3
	s_ashr_i32 s20, s19, 6
	v_ashrrev_i32_e32 v1, 31, v0
	v_add_u32_e32 v3, v138, v3
	s_add_u32 s41, s8, 0xc000000
	v_lshrrev_b32_e32 v1, 26, v1
	v_ashrrev_i32_e32 v3, 6, v3
	s_addc_u32 s42, s9, 0
	v_add_u32_e32 v1, v0, v1
	v_lshlrev_b32_e32 v4, 3, v3
	s_add_u32 s43, s8, 0x2f00000
	v_ashrrev_i32_e32 v2, 6, v1
	v_and_b32_e32 v4, -16, v4
	s_addc_u32 s44, s9, 0
	v_add_u32_e32 v4, v2, v4
	v_and_b32_e32 v2, 3, v2
	s_mov_b32 s0, 0x1fffe0
	s_sub_i32 s98, 0x15ff, s40
	s_ashr_i32 s46, s40, 31
	v_and_or_b32 v2, v4, s0, v2
	s_lshr_b32 s0, s46, 29
	s_add_i32 s0, s98, s0
	s_ashr_i32 s1, s0, 3
	s_and_b32 s0, s0, -8
	s_ashr_i32 s21, s19, 8
	s_lshl_b32 s45, s20, 10
	s_sub_i32 s0, s98, s0
	s_cmp_lt_i32 s0, 0
	s_movk_i32 s47, 0x2c1
	s_cselect_b32 s2, s47, 0x2c0
	s_mul_i32 s0, s0, s2
	s_add_i32 s0, s0, s1
	s_mul_hi_i32 s1, s0, 0x2e8ba2e9
	s_lshr_b32 s2, s1, 31
	s_ashr_i32 s1, s1, 5
	s_add_i32 s1, s1, s2
	s_lshl_b32 s2, s1, 3
	s_mulk_i32 s1, 0xb0
	s_sub_i32 s0, s0, s1
	s_bfe_u32 s1, s0, 0x3001c
	s_add_i32 s1, s0, s1
	s_sext_i32_i16 s3, s1
	s_and_b32 s1, s1, 0xfff8
	s_sub_i32 s0, s0, s1
	v_and_b32_e32 v1, 0xc0, v1
	s_sext_i32_i16 s0, s0
	v_sub_u32_e32 v0, v0, v1
	v_mov_b32_e32 v1, 1
	s_lshr_b32 s18, s3, 3
	s_add_i32 s28, s2, s0
	v_lshrrev_b32_e32 v5, 2, v4
	v_lshlrev_b32_e32 v6, 1, v4
	v_lshlrev_b32_e32 v3, 5, v3
	v_ashrrev_i16_sdwa v0, v1, sext(v0) dst_sel:DWORD dst_unused:UNUSED_PAD src0_sel:DWORD src1_sel:BYTE_0
	s_ashr_i32 s29, s28, 31
	s_bfe_i64 s[0:1], s[18:19], 0x100000
	v_and_b32_e32 v5, 4, v5
	v_and_b32_e32 v6, 24, v6
	v_and_b32_e32 v3, 32, v3
	v_bfe_i32 v0, v0, 0, 16
	s_lshl_b64 s[6:7], s[28:29], 19
	s_lshl_b64 s[0:1], s[0:1], 19
	v_or3_b32 v2, v2, v5, v6
	v_add_lshl_u32 v0, v3, v0, 1
	s_add_u32 s30, s43, s0
	v_lshl_add_u32 v128, v2, 11, v0
	s_addc_u32 s31, s44, s1
	v_mov_b32_e32 v129, 0
	s_add_i32 s48, s45, 0
	v_lshl_add_u32 v130, v4, 11, v0
	v_lshl_add_u64 v[0:1], s[30:31], 0, v[128:129]
	s_add_i32 m0, s48, 0x10000
	s_mov_b64 s[0:1], 0x20000
	global_load_lds_dwordx4 v128, s[30:31]
	v_lshl_add_u64 v[2:3], v[0:1], 0, s[0:1]
	s_add_i32 m0, s48, 0x12000
	s_mov_b64 s[2:3], 0x40000
	global_load_lds_dwordx4 v[2:3], off
	v_lshl_add_u64 v[2:3], v[0:1], 0, s[2:3]
	s_add_i32 m0, s48, 0x14000
	s_mov_b64 s[4:5], 0x60000
	global_load_lds_dwordx4 v[2:3], off
	s_add_i32 m0, s48, 0x16000
	s_add_u32 s34, s41, s6
	v_lshl_add_u64 v[2:3], v[0:1], 0, s[4:5]
	s_addc_u32 s35, s42, s7
	v_mov_b32_e32 v131, v129
	global_load_lds_dwordx4 v[2:3], off
	v_lshl_add_u64 v[2:3], s[34:35], 0, v[130:131]
	s_mov_b32 m0, s48
	s_add_i32 s49, s48, 0x2000
	global_load_lds_dwordx4 v130, s[34:35]
	v_lshl_add_u64 v[4:5], v[2:3], 0, s[0:1]
	s_mov_b32 m0, s49
	s_add_i32 s50, s48, 0x4000
	global_load_lds_dwordx4 v[4:5], off
	v_lshl_add_u64 v[4:5], v[2:3], 0, s[2:3]
	s_mov_b32 m0, s50
	s_add_i32 s51, s48, 0x6000
	global_load_lds_dwordx4 v[4:5], off
	v_lshl_add_u64 v[4:5], v[2:3], 0, s[4:5]
	s_mov_b32 m0, s51
	s_cmp_eq_u32 s21, 1
	global_load_lds_dwordx4 v[4:5], off
	s_cselect_b64 s[6:7], -1, 0
	s_cmp_lg_u32 s21, 1
	s_mov_b32 s52, 0
	s_cbranch_scc1 .LBB0_964
	s_barrier

.LBB0_967:
	s_add_i32 s52, s52, 1
	s_mul_i32 s21, s52, s57
	s_mul_hi_u32 s23, s52, s33
	s_add_i32 s23, s23, s21
	s_mul_i32 s21, s52, s33
	s_add_u32 s24, s21, s40
	s_addc_u32 s25, s23, s46
	v_cmp_gt_i64_e32 vcc, s[24:25], v[134:135]
	v_cmp_lt_i64_e64 s[36:37], s[24:25], v[132:133]
	s_cbranch_vccnz .LBB0_969
	s_sub_i32 s24, 0x15ff, s24
	s_ashr_i32 s20, s24, 31
	s_lshr_b32 s20, s20, 29
	s_add_i32 s20, s24, s20
	s_ashr_i32 s21, s20, 3
	s_and_b32 s20, s20, -8
	s_sub_i32 s20, s24, s20
	s_cmp_lt_i32 s20, 0
	s_cselect_b32 s22, s47, 0x2c0
	s_mul_i32 s20, s20, s22
	s_add_i32 s20, s20, s21
	s_mul_hi_i32 s21, s20, 0x2e8ba2e9
	s_lshr_b32 s22, s21, 31
	s_ashr_i32 s21, s21, 5
	s_add_i32 s21, s21, s22
	s_lshl_b32 s22, s21, 3
	s_sub_i32 s23, 0x100, s22
	s_min_i32 s23, s23, 8
	s_abs_i32 s24, s23
	v_cvt_f32_u32_e32 v0, s24
	s_sub_i32 s26, 0, s24
	s_mulk_i32 s21, 0xb0
	s_sub_i32 s21, s20, s21
	v_rcp_iflag_f32_e32 v0, v0
	s_abs_i32 s20, s21
	s_xor_b32 s25, s21, s23
	s_ashr_i32 s25, s25, 31
	v_mul_f32_e32 v0, 0x4f7ffffe, v0
	v_cvt_u32_f32_e32 v0, v0
	s_nop 0
	v_readfirstlane_b32 s27, v0
	s_mul_i32 s26, s26, s27
	s_mul_hi_u32 s26, s27, s26
	s_add_i32 s27, s27, s26
	s_mul_hi_u32 s26, s20, s27
	s_mul_i32 s27, s26, s24
	s_sub_i32 s20, s20, s27
	s_add_i32 s38, s26, 1
	s_sub_i32 s27, s20, s24
	s_cmp_ge_u32 s20, s24
	s_cselect_b32 s26, s38, s26
	s_cselect_b32 s20, s27, s20
	s_add_i32 s27, s26, 1
	s_cmp_ge_u32 s20, s24
	s_cselect_b32 s20, s27, s26
	s_xor_b32 s20, s20, s25
	s_sub_i32 s20, s20, s25
	s_mul_i32 s23, s20, s23
	s_sub_i32 s21, s21, s23
	s_add_i32 s22, s22, s21
